# FFN-up K-loop: closing barrier of each 16-MFMA block issued before its last 4 MFMAs (hand-off overlap)
# baseline (speedup 1.0000x reference)
; #define PG8_STAGE(bufoff, gbase, voff) do { _Pragma("unroll") for (int _i = 0; _i < 2; ++_i) \
;         __builtin_amdgcn_global_load_lds((const unsigned*)((const char*)(gbase) + (voff)[_i]), (LAS unsigned*)(lds + (bufoff) + ldsw + _i * 8192), 16, 0, 0); } while (0)
; #define PG8_LDA(dst, b, h) do { _Pragma("unroll") for (int m = 0; m < 4; ++m) _Pragma("unroll") for (int k = 0; k < 2; ++k) dst[m][k] = *(const LAS bf16x8*)(lds + PG8_SA(b, h) + aoff + m * 2048 + k * 1024); } while (0)
; #define PG8_LDB(dst, b, h) do { _Pragma("unroll") for (int n = 0; n < 2; ++n) _Pragma("unroll") for (int k = 0; k < 2; ++k) dst[n][k] = *(const LAS bf16x8*)(lds + PG8_SB(b, h) + boff + n * 2048 + k * 1024); } while (0)
; #define PG8_MMA(ai, bj, At, Bt) do { __builtin_amdgcn_s_setprio(1); _Pragma("unroll") for (int m = 0; m < 4; ++m) _Pragma("unroll") for (int n = 0; n < 2; ++n) _Pragma("unroll") for (int k = 0; k < 2; ++k) \
;         acc[ai][bj][m][n] = __builtin_amdgcn_mfma_f32_16x16x32_bf16(Bt[n][k], At[m][k], acc[ai][bj][m][n], 0, 0, 0); __builtin_amdgcn_s_setprio(0); } while (0)
; #define PG8_WAIT_V(n) asm volatile("s_waitcnt vmcnt(" #n ")" ::: "memory")
; #define PG8_WAIT_L(n) asm volatile("s_waitcnt lgkmcnt(" #n ")" ::: "memory")
; #define PG8_BAR __builtin_amdgcn_s_barrier()
; #define PG8_SCHED __builtin_amdgcn_sched_barrier(0)
; template <class Epi, class Sched>
; __device__ __forceinline__ void gemm_phase(LAS unsigned char* lds, const int K, const Sched& S, const Epi& E) {
;     ...
;             PG8_LDB(B0, 0, 0); PG8_SCHED; PG8_LDA(At, 0, 0); PG8_STAGE(PG8_SA(1, 1), a1 + hstepA, voffA);
;             PG8_WAIT_L(8); PG8_BAR; PG8_WAIT_L(0); PG8_MMA(0, 0, At, B0); PG8_BAR; PG8_SCHED;
;             PG8_LDB(B1, 0, 1); PG8_STAGE(PG8_SB(0, 0), b2, voffB);
;             PG8_BAR; PG8_WAIT_L(0); PG8_MMA(0, 1, At, B1); PG8_BAR;
;             PG8_LDA(At, 0, 1); PG8_STAGE(PG8_SA(0, 0), a2, voffA);
;             PG8_BAR; PG8_WAIT_L(0); PG8_MMA(1, 0, At, B0); PG8_BAR; PG8_SCHED;
;             PG8_STAGE(PG8_SB(0, 1), b2 + hstep, voffB);
;             PG8_WAIT_V(6); PG8_BAR; PG8_MMA(1, 1, At, B1); PG8_BAR;
.Lpeel_p7:
	ds_read_b128 v[128:131], v158
	ds_read_b128 v[132:135], v158 offset:1024
	ds_read_b128 v[148:151], v158 offset:2048
	ds_read_b128 v[162:165], v158 offset:3072
	s_add_u32 s68, s12, 0x100
	s_addc_u32 s69, s13, 0
	s_cmp_eq_u32 s49, 12
	s_cselect_b32 s73, s63, s69
	s_cselect_b32 s72, s62, s68
	s_cselect_b32 s71, s65, s33
	s_cselect_b32 s70, s64, s11
	v_lshl_add_u64 v[200:201], s[12:13], 0, v[144:145]
	s_add_i32 m0, s67, 0xc000
	ds_read_b128 v[166:169], v159
	ds_read_b128 v[172:175], v159 offset:1024
	ds_read_b128 v[176:179], v159 offset:2048
	ds_read_b128 v[180:183], v159 offset:3072
	ds_read_b128 v[184:187], v159 offset:4096
	ds_read_b128 v[188:191], v159 offset:5120
	ds_read_b128 v[192:195], v159 offset:6144
	ds_read_b128 v[196:199], v159 offset:7168
	global_load_lds_dwordx4 v[200:201], off
	v_lshl_add_u64 v[200:201], s[12:13], 0, v[146:147]
	s_add_i32 m0, s67, 0xe000
	s_nop 0
	global_load_lds_dwordx4 v[200:201], off
	s_waitcnt lgkmcnt(8)
	s_barrier
	s_waitcnt lgkmcnt(0)
	s_setprio 1
	s_waitcnt lgkmcnt(0)
	v_mfma_f32_16x16x32_bf16 v[84:87], v[128:131], v[166:169], 0
	v_mfma_f32_16x16x32_bf16 v[76:79], v[148:151], v[166:169], 0
	v_mfma_f32_16x16x32_bf16 v[124:127], v[128:131], v[176:179], 0
	v_mfma_f32_16x16x32_bf16 v[72:75], v[148:151], v[176:179], 0
	v_mfma_f32_16x16x32_bf16 v[120:123], v[128:131], v[184:187], 0
	v_mfma_f32_16x16x32_bf16 v[96:99], v[148:151], v[184:187], 0
	v_mfma_f32_16x16x32_bf16 v[116:119], v[128:131], v[192:195], 0
	v_mfma_f32_16x16x32_bf16 v[92:95], v[148:151], v[192:195], 0
	v_mfma_f32_16x16x32_bf16 v[84:87], v[132:135], v[172:175], v[84:87]
	v_mfma_f32_16x16x32_bf16 v[76:79], v[162:165], v[172:175], v[76:79]
	v_mfma_f32_16x16x32_bf16 v[124:127], v[132:135], v[180:183], v[124:127]
	v_mfma_f32_16x16x32_bf16 v[72:75], v[162:165], v[180:183], v[72:75]
	s_barrier
	v_mfma_f32_16x16x32_bf16 v[120:123], v[132:135], v[188:191], v[120:123]
	v_mfma_f32_16x16x32_bf16 v[96:99], v[162:165], v[188:191], v[96:99]
	v_mfma_f32_16x16x32_bf16 v[116:119], v[132:135], v[196:199], v[116:119]
	v_mfma_f32_16x16x32_bf16 v[92:95], v[162:165], v[196:199], v[92:95]
	s_setprio 0
	s_add_i32 s12, s88, s78
	v_lshl_add_u64 v[216:217], s[70:71], 0, v[138:139]
	s_mov_b32 m0, s12
	ds_read_b128 v[200:203], v160
	ds_read_b128 v[204:207], v160 offset:1024
	ds_read_b128 v[208:211], v160 offset:2048
	ds_read_b128 v[212:215], v160 offset:3072
	global_load_lds_dwordx4 v[216:217], off
	v_lshl_add_u64 v[218:219], s[70:71], 0, v[142:143]
	s_add_i32 m0, s12, 0x2000
	s_nop 0
	global_load_lds_dwordx4 v[218:219], off
	s_barrier
	s_waitcnt lgkmcnt(0)
	s_setprio 1
	s_waitcnt lgkmcnt(0)
	v_mfma_f32_16x16x32_bf16 v[60:63], v[200:203], v[166:169], 0
	v_mfma_f32_16x16x32_bf16 v[16:19], v[208:211], v[166:169], 0
	v_mfma_f32_16x16x32_bf16 v[56:59], v[200:203], v[176:179], 0
	v_mfma_f32_16x16x32_bf16 v[12:15], v[208:211], v[176:179], 0
	v_mfma_f32_16x16x32_bf16 v[52:55], v[200:203], v[184:187], 0
	v_mfma_f32_16x16x32_bf16 v[28:31], v[208:211], v[184:187], 0
	v_mfma_f32_16x16x32_bf16 v[48:51], v[200:203], v[192:195], 0
	v_mfma_f32_16x16x32_bf16 v[24:27], v[208:211], v[192:195], 0
	v_mfma_f32_16x16x32_bf16 v[60:63], v[204:207], v[172:175], v[60:63]
	v_mfma_f32_16x16x32_bf16 v[16:19], v[212:215], v[172:175], v[16:19]
	v_mfma_f32_16x16x32_bf16 v[56:59], v[204:207], v[180:183], v[56:59]
	v_mfma_f32_16x16x32_bf16 v[12:15], v[212:215], v[180:183], v[12:15]
	s_barrier
	v_mfma_f32_16x16x32_bf16 v[52:55], v[204:207], v[188:191], v[52:55]
	v_mfma_f32_16x16x32_bf16 v[28:31], v[212:215], v[188:191], v[28:31]
	v_mfma_f32_16x16x32_bf16 v[48:51], v[204:207], v[196:199], v[48:51]
	v_mfma_f32_16x16x32_bf16 v[24:27], v[212:215], v[196:199], v[24:27]
	s_setprio 0
	s_mov_b32 m0, s67
	v_lshl_add_u64 v[220:221], s[72:73], 0, v[136:137]
	ds_read_b128 v[166:169], v159 offset:16384
	ds_read_b128 v[172:175], v159 offset:17408
	ds_read_b128 v[176:179], v159 offset:18432
	ds_read_b128 v[180:183], v159 offset:19456
	ds_read_b128 v[184:187], v159 offset:20480
	ds_read_b128 v[188:191], v159 offset:21504
	ds_read_b128 v[192:195], v159 offset:22528
	ds_read_b128 v[196:199], v159 offset:23552
	global_load_lds_dwordx4 v[220:221], off
	v_lshl_add_u64 v[222:223], s[72:73], 0, v[140:141]
	s_mov_b32 m0, s80
	s_nop 0
	global_load_lds_dwordx4 v[222:223], off
	s_barrier
	s_waitcnt lgkmcnt(0)
	s_setprio 1
	s_waitcnt lgkmcnt(0)
	v_mfma_f32_16x16x32_bf16 v[112:115], v[128:131], v[166:169], 0
	v_mfma_f32_16x16x32_bf16 v[88:91], v[148:151], v[166:169], 0
	v_mfma_f32_16x16x32_bf16 v[104:107], v[128:131], v[176:179], 0
	v_mfma_f32_16x16x32_bf16 v[80:83], v[148:151], v[176:179], 0
	v_mfma_f32_16x16x32_bf16 v[100:103], v[128:131], v[184:187], 0
	v_mfma_f32_16x16x32_bf16 v[64:67], v[148:151], v[184:187], 0
	v_mfma_f32_16x16x32_bf16 v[108:111], v[128:131], v[192:195], 0
	v_mfma_f32_16x16x32_bf16 v[68:71], v[148:151], v[192:195], 0
	v_mfma_f32_16x16x32_bf16 v[112:115], v[132:135], v[172:175], v[112:115]
	v_mfma_f32_16x16x32_bf16 v[88:91], v[162:165], v[172:175], v[88:91]
	v_mfma_f32_16x16x32_bf16 v[104:107], v[132:135], v[180:183], v[104:107]
	v_mfma_f32_16x16x32_bf16 v[80:83], v[162:165], v[180:183], v[80:83]
	s_barrier
	v_mfma_f32_16x16x32_bf16 v[100:103], v[132:135], v[188:191], v[100:103]
	v_mfma_f32_16x16x32_bf16 v[64:67], v[162:165], v[188:191], v[64:67]
	v_mfma_f32_16x16x32_bf16 v[108:111], v[132:135], v[196:199], v[108:111]
	v_mfma_f32_16x16x32_bf16 v[68:71], v[162:165], v[196:199], v[68:71]
	s_setprio 0
	s_add_u32 s12, s70, 0x40000
	s_addc_u32 s13, s71, 0
	s_add_i32 s52, s89, s78
	v_lshl_add_u64 v[128:129], s[12:13], 0, v[138:139]
	s_mov_b32 m0, s52
	s_nop 0
	global_load_lds_dwordx4 v[128:129], off
	v_lshl_add_u64 v[128:129], s[12:13], 0, v[142:143]
	s_add_i32 m0, s52, 0x2000
	s_nop 0
	global_load_lds_dwordx4 v[128:129], off
	s_waitcnt vmcnt(6)
	s_barrier
; #define PG8_STAGE(bufoff, gbase, voff) do { _Pragma("unroll") for (int _i = 0; _i < 2; ++_i) \
;         __builtin_amdgcn_global_load_lds((const unsigned*)((const char*)(gbase) + (voff)[_i]), (LAS unsigned*)(lds + (bufoff) + ldsw + _i * 8192), 16, 0, 0); } while (0)
; #define PG8_LDA(dst, b, h) do { _Pragma("unroll") for (int m = 0; m < 4; ++m) _Pragma("unroll") for (int k = 0; k < 2; ++k) dst[m][k] = *(const LAS bf16x8*)(lds + PG8_SA(b, h) + aoff + m * 2048 + k * 1024); } while (0)
; #define PG8_LDB(dst, b, h) do { _Pragma("unroll") for (int n = 0; n < 2; ++n) _Pragma("unroll") for (int k = 0; k < 2; ++k) dst[n][k] = *(const LAS bf16x8*)(lds + PG8_SB(b, h) + boff + n * 2048 + k * 1024); } while (0)
; #define PG8_MMA(ai, bj, At, Bt) do { __builtin_amdgcn_s_setprio(1); _Pragma("unroll") for (int m = 0; m < 4; ++m) _Pragma("unroll") for (int n = 0; n < 2; ++n) _Pragma("unroll") for (int k = 0; k < 2; ++k) \
;         acc[ai][bj][m][n] = __builtin_amdgcn_mfma_f32_16x16x32_bf16(Bt[n][k], At[m][k], acc[ai][bj][m][n], 0, 0, 0); __builtin_amdgcn_s_setprio(0); } while (0)
; #define PG8_WAIT_V(n) asm volatile("s_waitcnt vmcnt(" #n ")" ::: "memory")
; #define PG8_WAIT_L(n) asm volatile("s_waitcnt lgkmcnt(" #n ")" ::: "memory")
; #define PG8_BAR __builtin_amdgcn_s_barrier()
; #define PG8_SCHED __builtin_amdgcn_sched_barrier(0)
; template <class Epi, class Sched>
; __device__ __forceinline__ void gemm_phase(LAS unsigned char* lds, const int K, const Sched& S, const Epi& E) {
;     ...
;             PG8_WAIT_V(6); PG8_BAR; PG8_MMA(1, 1, At, B1); PG8_BAR;
;             PG8_LDB(B0, 1, 0); PG8_SCHED; PG8_LDA(At, 1, 0); PG8_STAGE(PG8_SA(0, 1), a2 + hstepA, voffA);
;             PG8_WAIT_L(8); PG8_BAR; PG8_WAIT_L(0); PG8_MMA(0, 0, At, B0); PG8_BAR; PG8_SCHED;
;             PG8_LDB(B1, 1, 1); PG8_STAGE(PG8_SB(1, 0), b3, voffB);
;             PG8_BAR; PG8_WAIT_L(0); PG8_MMA(0, 1, At, B1); PG8_BAR;
;             PG8_LDA(At, 1, 1); PG8_STAGE(PG8_SA(1, 0), a3, voffA);
;             PG8_BAR; PG8_WAIT_L(0); PG8_MMA(1, 0, At, B0); PG8_BAR; PG8_SCHED;
	s_setprio 1
	v_mfma_f32_16x16x32_bf16 v[44:47], v[200:203], v[166:169], 0
	v_mfma_f32_16x16x32_bf16 v[20:23], v[208:211], v[166:169], 0
	v_mfma_f32_16x16x32_bf16 v[40:43], v[200:203], v[176:179], 0
	v_mfma_f32_16x16x32_bf16 v[8:11], v[208:211], v[176:179], 0
	v_mfma_f32_16x16x32_bf16 v[36:39], v[200:203], v[184:187], 0
	v_mfma_f32_16x16x32_bf16 v[0:3], v[208:211], v[184:187], 0
	v_mfma_f32_16x16x32_bf16 v[32:35], v[200:203], v[192:195], 0
	v_mfma_f32_16x16x32_bf16 v[4:7], v[208:211], v[192:195], 0
	v_mfma_f32_16x16x32_bf16 v[44:47], v[204:207], v[172:175], v[44:47]
	v_mfma_f32_16x16x32_bf16 v[20:23], v[212:215], v[172:175], v[20:23]
	v_mfma_f32_16x16x32_bf16 v[40:43], v[204:207], v[180:183], v[40:43]
	v_mfma_f32_16x16x32_bf16 v[8:11], v[212:215], v[180:183], v[8:11]
	s_barrier
	v_mfma_f32_16x16x32_bf16 v[36:39], v[204:207], v[188:191], v[36:39]
	v_mfma_f32_16x16x32_bf16 v[0:3], v[212:215], v[188:191], v[0:3]
	v_mfma_f32_16x16x32_bf16 v[32:35], v[204:207], v[196:199], v[32:35]
	v_mfma_f32_16x16x32_bf16 v[4:7], v[212:215], v[196:199], v[4:7]
	s_setprio 0
	s_add_i32 s52, 0, 0x18000
	v_add_u32_e32 v161, s52, v156
	ds_read_b128 v[128:131], v161
	ds_read_b128 v[132:135], v161 offset:1024
	ds_read_b128 v[148:151], v161 offset:2048
	ds_read_b128 v[162:165], v161 offset:3072
	s_add_u32 s12, s72, 0x20000
	s_addc_u32 s13, s73, 0
	s_mov_b32 m0, s81
	v_lshl_add_u64 v[200:201], s[12:13], 0, v[136:137]
	ds_read_b128 v[166:169], v159 offset:32768
	ds_read_b128 v[172:175], v159 offset:33792
	ds_read_b128 v[176:179], v159 offset:34816
	ds_read_b128 v[180:183], v159 offset:35840
	ds_read_b128 v[184:187], v159 offset:36864
	ds_read_b128 v[188:191], v159 offset:37888
	ds_read_b128 v[192:195], v159 offset:38912
	ds_read_b128 v[196:199], v159 offset:39936
	global_load_lds_dwordx4 v[200:201], off
	v_lshl_add_u64 v[200:201], s[12:13], 0, v[140:141]
	s_mov_b32 m0, s82
	s_nop 0
	global_load_lds_dwordx4 v[200:201], off
	s_waitcnt lgkmcnt(8)
	s_barrier
	s_waitcnt lgkmcnt(0)
	s_setprio 1
	s_waitcnt lgkmcnt(0)
	v_mfma_f32_16x16x32_bf16 v[84:87], v[128:131], v[166:169], v[84:87]
	v_mfma_f32_16x16x32_bf16 v[76:79], v[148:151], v[166:169], v[76:79]
	v_mfma_f32_16x16x32_bf16 v[124:127], v[128:131], v[176:179], v[124:127]
	v_mfma_f32_16x16x32_bf16 v[72:75], v[148:151], v[176:179], v[72:75]
	v_mfma_f32_16x16x32_bf16 v[120:123], v[128:131], v[184:187], v[120:123]
	v_mfma_f32_16x16x32_bf16 v[96:99], v[148:151], v[184:187], v[96:99]
	v_mfma_f32_16x16x32_bf16 v[116:119], v[128:131], v[192:195], v[116:119]
	v_mfma_f32_16x16x32_bf16 v[92:95], v[148:151], v[192:195], v[92:95]
	v_mfma_f32_16x16x32_bf16 v[84:87], v[132:135], v[172:175], v[84:87]
	v_mfma_f32_16x16x32_bf16 v[76:79], v[162:165], v[172:175], v[76:79]
	v_mfma_f32_16x16x32_bf16 v[124:127], v[132:135], v[180:183], v[124:127]
	v_mfma_f32_16x16x32_bf16 v[72:75], v[162:165], v[180:183], v[72:75]
	s_barrier
	v_mfma_f32_16x16x32_bf16 v[120:123], v[132:135], v[188:191], v[120:123]
	v_mfma_f32_16x16x32_bf16 v[96:99], v[162:165], v[188:191], v[96:99]
	v_mfma_f32_16x16x32_bf16 v[116:119], v[132:135], v[196:199], v[116:119]
	v_mfma_f32_16x16x32_bf16 v[92:95], v[162:165], v[196:199], v[92:95]
	s_setprio 0
	s_add_i32 s53, 0, 0x1c000
	s_add_i32 s12, s52, s78
	v_add_u32_e32 v161, s53, v156
	v_lshl_add_u64 v[216:217], v[216:217], 0, s[38:39]
	s_mov_b32 m0, s12
	ds_read_b128 v[200:203], v161
	ds_read_b128 v[204:207], v161 offset:1024
	ds_read_b128 v[208:211], v161 offset:2048
	ds_read_b128 v[212:215], v161 offset:3072
	global_load_lds_dwordx4 v[216:217], off
	v_lshl_add_u64 v[216:217], v[218:219], 0, s[38:39]
	s_add_i32 m0, s12, 0x2000
	s_nop 0
	global_load_lds_dwordx4 v[216:217], off
	s_barrier
	s_waitcnt lgkmcnt(0)
	s_setprio 1
	s_waitcnt lgkmcnt(0)
	v_mfma_f32_16x16x32_bf16 v[60:63], v[200:203], v[166:169], v[60:63]
	v_mfma_f32_16x16x32_bf16 v[16:19], v[208:211], v[166:169], v[16:19]
	v_mfma_f32_16x16x32_bf16 v[56:59], v[200:203], v[176:179], v[56:59]
	v_mfma_f32_16x16x32_bf16 v[12:15], v[208:211], v[176:179], v[12:15]
	v_mfma_f32_16x16x32_bf16 v[52:55], v[200:203], v[184:187], v[52:55]
	v_mfma_f32_16x16x32_bf16 v[28:31], v[208:211], v[184:187], v[28:31]
	v_mfma_f32_16x16x32_bf16 v[48:51], v[200:203], v[192:195], v[48:51]
	v_mfma_f32_16x16x32_bf16 v[24:27], v[208:211], v[192:195], v[24:27]
	v_mfma_f32_16x16x32_bf16 v[60:63], v[204:207], v[172:175], v[60:63]
	v_mfma_f32_16x16x32_bf16 v[16:19], v[212:215], v[172:175], v[16:19]
	v_mfma_f32_16x16x32_bf16 v[56:59], v[204:207], v[180:183], v[56:59]
	v_mfma_f32_16x16x32_bf16 v[12:15], v[212:215], v[180:183], v[12:15]
	s_barrier
	v_mfma_f32_16x16x32_bf16 v[52:55], v[204:207], v[188:191], v[52:55]
	v_mfma_f32_16x16x32_bf16 v[28:31], v[212:215], v[188:191], v[28:31]
	v_mfma_f32_16x16x32_bf16 v[48:51], v[204:207], v[196:199], v[48:51]
	v_mfma_f32_16x16x32_bf16 v[24:27], v[212:215], v[196:199], v[24:27]
	s_setprio 0
	s_mov_b32 m0, s84
	v_lshl_add_u64 v[216:217], v[220:221], 0, s[38:39]
	ds_read_b128 v[166:169], v159 offset:49152
	ds_read_b128 v[172:175], v159 offset:50176
	ds_read_b128 v[176:179], v159 offset:51200
	ds_read_b128 v[180:183], v159 offset:52224
	ds_read_b128 v[184:187], v159 offset:53248
	ds_read_b128 v[188:191], v159 offset:54272
	ds_read_b128 v[192:195], v159 offset:55296
	ds_read_b128 v[196:199], v159 offset:56320
	global_load_lds_dwordx4 v[216:217], off
	v_lshl_add_u64 v[216:217], v[222:223], 0, s[38:39]
	s_mov_b32 m0, s85
	s_nop 0
	global_load_lds_dwordx4 v[216:217], off
	s_barrier
; #define PG8_STAGE(bufoff, gbase, voff) do { _Pragma("unroll") for (int _i = 0; _i < 2; ++_i) \
;         __builtin_amdgcn_global_load_lds((const unsigned*)((const char*)(gbase) + (voff)[_i]), (LAS unsigned*)(lds + (bufoff) + ldsw + _i * 8192), 16, 0, 0); } while (0)
; #define PG8_LDA(dst, b, h) do { _Pragma("unroll") for (int m = 0; m < 4; ++m) _Pragma("unroll") for (int k = 0; k < 2; ++k) dst[m][k] = *(const LAS bf16x8*)(lds + PG8_SA(b, h) + aoff + m * 2048 + k * 1024); } while (0)
; #define PG8_LDB(dst, b, h) do { _Pragma("unroll") for (int n = 0; n < 2; ++n) _Pragma("unroll") for (int k = 0; k < 2; ++k) dst[n][k] = *(const LAS bf16x8*)(lds + PG8_SB(b, h) + boff + n * 2048 + k * 1024); } while (0)
; #define PG8_MMA(ai, bj, At, Bt) do { __builtin_amdgcn_s_setprio(1); _Pragma("unroll") for (int m = 0; m < 4; ++m) _Pragma("unroll") for (int n = 0; n < 2; ++n) _Pragma("unroll") for (int k = 0; k < 2; ++k) \
;         acc[ai][bj][m][n] = __builtin_amdgcn_mfma_f32_16x16x32_bf16(Bt[n][k], At[m][k], acc[ai][bj][m][n], 0, 0, 0); __builtin_amdgcn_s_setprio(0); } while (0)
; #define PG8_WAIT_V(n) asm volatile("s_waitcnt vmcnt(" #n ")" ::: "memory")
; #define PG8_WAIT_L(n) asm volatile("s_waitcnt lgkmcnt(" #n ")" ::: "memory")
; #define PG8_BAR __builtin_amdgcn_s_barrier()
; #define PG8_SCHED __builtin_amdgcn_sched_barrier(0)
; template <class Epi, class Sched>
; __device__ __forceinline__ void gemm_phase(LAS unsigned char* lds, const int K, const Sched& S, const Epi& E) {
;     ...
;             PG8_LDB(B0, 0, 0); PG8_SCHED; PG8_LDA(At, 0, 0); PG8_STAGE(PG8_SA(1, 1), a1 + hstepA, voffA);
;             PG8_WAIT_L(8); PG8_BAR; PG8_WAIT_L(0); PG8_MMA(0, 0, At, B0); PG8_BAR; PG8_SCHED;
;             PG8_LDB(B1, 0, 1); PG8_STAGE(PG8_SB(0, 0), b2, voffB);
;     ...
;             PG8_BAR; PG8_WAIT_L(0); PG8_MMA(1, 0, At, B0); PG8_BAR; PG8_SCHED;
;             PG8_STAGE(PG8_SB(1, 1), b3 + hstep, voffB);
;             PG8_WAIT_V(6); PG8_BAR; PG8_MMA(1, 1, At, B1); PG8_BAR;
	s_waitcnt lgkmcnt(0)
	s_setprio 1
	s_waitcnt lgkmcnt(0)
	v_mfma_f32_16x16x32_bf16 v[112:115], v[128:131], v[166:169], v[112:115]
	v_mfma_f32_16x16x32_bf16 v[88:91], v[148:151], v[166:169], v[88:91]
	v_mfma_f32_16x16x32_bf16 v[104:107], v[128:131], v[176:179], v[104:107]
	v_mfma_f32_16x16x32_bf16 v[80:83], v[148:151], v[176:179], v[80:83]
	v_mfma_f32_16x16x32_bf16 v[100:103], v[128:131], v[184:187], v[100:103]
	v_mfma_f32_16x16x32_bf16 v[64:67], v[148:151], v[184:187], v[64:67]
	v_mfma_f32_16x16x32_bf16 v[108:111], v[128:131], v[192:195], v[108:111]
	v_mfma_f32_16x16x32_bf16 v[68:71], v[148:151], v[192:195], v[68:71]
	v_mfma_f32_16x16x32_bf16 v[112:115], v[132:135], v[172:175], v[112:115]
	v_mfma_f32_16x16x32_bf16 v[88:91], v[162:165], v[172:175], v[88:91]
	v_mfma_f32_16x16x32_bf16 v[104:107], v[132:135], v[180:183], v[104:107]
	v_mfma_f32_16x16x32_bf16 v[80:83], v[162:165], v[180:183], v[80:83]
	s_barrier
	v_mfma_f32_16x16x32_bf16 v[100:103], v[132:135], v[188:191], v[100:103]
	v_mfma_f32_16x16x32_bf16 v[64:67], v[162:165], v[188:191], v[64:67]
	v_mfma_f32_16x16x32_bf16 v[108:111], v[132:135], v[196:199], v[108:111]
	v_mfma_f32_16x16x32_bf16 v[68:71], v[162:165], v[196:199], v[68:71]
	s_setprio 0
	s_add_u32 s12, s70, 0x40080
	s_addc_u32 s13, s71, 0
	s_add_i32 s52, s53, s78
	v_lshl_add_u64 v[128:129], s[12:13], 0, v[138:139]
	s_mov_b32 m0, s52
	s_nop 0
	global_load_lds_dwordx4 v[128:129], off
	v_lshl_add_u64 v[128:129], s[12:13], 0, v[142:143]
	s_add_i32 m0, s52, 0x2000
	s_nop 0
	global_load_lds_dwordx4 v[128:129], off
	s_waitcnt vmcnt(6)
	s_barrier
	s_setprio 1
	v_mfma_f32_16x16x32_bf16 v[44:47], v[200:203], v[166:169], v[44:47]
	v_mfma_f32_16x16x32_bf16 v[20:23], v[208:211], v[166:169], v[20:23]
	v_mfma_f32_16x16x32_bf16 v[40:43], v[200:203], v[176:179], v[40:43]
	v_mfma_f32_16x16x32_bf16 v[8:11], v[208:211], v[176:179], v[8:11]
	v_mfma_f32_16x16x32_bf16 v[36:39], v[200:203], v[184:187], v[36:39]
	v_mfma_f32_16x16x32_bf16 v[0:3], v[208:211], v[184:187], v[0:3]
	v_mfma_f32_16x16x32_bf16 v[32:35], v[200:203], v[192:195], v[32:35]
	v_mfma_f32_16x16x32_bf16 v[4:7], v[208:211], v[192:195], v[4:7]
	v_mfma_f32_16x16x32_bf16 v[44:47], v[204:207], v[172:175], v[44:47]
	v_mfma_f32_16x16x32_bf16 v[20:23], v[212:215], v[172:175], v[20:23]
	v_mfma_f32_16x16x32_bf16 v[40:43], v[204:207], v[180:183], v[40:43]
	v_mfma_f32_16x16x32_bf16 v[8:11], v[212:215], v[180:183], v[8:11]
	s_barrier
	v_mfma_f32_16x16x32_bf16 v[36:39], v[204:207], v[188:191], v[36:39]
	v_mfma_f32_16x16x32_bf16 v[0:3], v[212:215], v[188:191], v[0:3]
	v_mfma_f32_16x16x32_bf16 v[32:35], v[204:207], v[196:199], v[32:35]
	v_mfma_f32_16x16x32_bf16 v[4:7], v[212:215], v[196:199], v[4:7]
	s_setprio 0
	s_add_i32 s49, s49, 2
	s_add_u32 s11, s11, 0x100
	s_addc_u32 s33, s33, 0
	s_cmp_gt_u32 s49, 13
	s_mov_b64 s[12:13], s[68:69]
.LBB0_800:
	ds_read_b128 v[128:131], v158
	ds_read_b128 v[132:135], v158 offset:1024
	ds_read_b128 v[148:151], v158 offset:2048
	ds_read_b128 v[162:165], v158 offset:3072
	s_add_u32 s68, s12, 0x100
	s_addc_u32 s69, s13, 0
	s_cmp_eq_u32 s49, 12
	s_cselect_b32 s73, s63, s69
	s_cselect_b32 s72, s62, s68
	s_cselect_b32 s71, s65, s33
	s_cselect_b32 s70, s64, s11
	v_lshl_add_u64 v[200:201], s[12:13], 0, v[144:145]
	s_add_i32 m0, s67, 0xc000
	ds_read_b128 v[166:169], v159
	ds_read_b128 v[172:175], v159 offset:1024
	ds_read_b128 v[176:179], v159 offset:2048
	ds_read_b128 v[180:183], v159 offset:3072
	ds_read_b128 v[184:187], v159 offset:4096
	ds_read_b128 v[188:191], v159 offset:5120
	ds_read_b128 v[192:195], v159 offset:6144
	ds_read_b128 v[196:199], v159 offset:7168
	global_load_lds_dwordx4 v[200:201], off
	v_lshl_add_u64 v[200:201], s[12:13], 0, v[146:147]
	s_add_i32 m0, s67, 0xe000
	s_nop 0
	global_load_lds_dwordx4 v[200:201], off
	s_waitcnt lgkmcnt(8)
	s_barrier
	s_waitcnt lgkmcnt(0)
	s_setprio 1
	s_waitcnt lgkmcnt(0)
	v_mfma_f32_16x16x32_bf16 v[84:87], v[128:131], v[166:169], v[84:87]
	v_mfma_f32_16x16x32_bf16 v[76:79], v[148:151], v[166:169], v[76:79]
	v_mfma_f32_16x16x32_bf16 v[124:127], v[128:131], v[176:179], v[124:127]
	v_mfma_f32_16x16x32_bf16 v[72:75], v[148:151], v[176:179], v[72:75]
	v_mfma_f32_16x16x32_bf16 v[120:123], v[128:131], v[184:187], v[120:123]
	v_mfma_f32_16x16x32_bf16 v[96:99], v[148:151], v[184:187], v[96:99]
	v_mfma_f32_16x16x32_bf16 v[116:119], v[128:131], v[192:195], v[116:119]
	v_mfma_f32_16x16x32_bf16 v[92:95], v[148:151], v[192:195], v[92:95]
	v_mfma_f32_16x16x32_bf16 v[84:87], v[132:135], v[172:175], v[84:87]
	v_mfma_f32_16x16x32_bf16 v[76:79], v[162:165], v[172:175], v[76:79]
	v_mfma_f32_16x16x32_bf16 v[124:127], v[132:135], v[180:183], v[124:127]
	v_mfma_f32_16x16x32_bf16 v[72:75], v[162:165], v[180:183], v[72:75]
	s_barrier
	v_mfma_f32_16x16x32_bf16 v[120:123], v[132:135], v[188:191], v[120:123]
	v_mfma_f32_16x16x32_bf16 v[96:99], v[162:165], v[188:191], v[96:99]
	v_mfma_f32_16x16x32_bf16 v[116:119], v[132:135], v[196:199], v[116:119]
	v_mfma_f32_16x16x32_bf16 v[92:95], v[162:165], v[196:199], v[92:95]
	s_setprio 0
	s_add_i32 s12, s88, s78
	v_lshl_add_u64 v[216:217], s[70:71], 0, v[138:139]
	s_mov_b32 m0, s12
	ds_read_b128 v[200:203], v160
	ds_read_b128 v[204:207], v160 offset:1024
	ds_read_b128 v[208:211], v160 offset:2048
	ds_read_b128 v[212:215], v160 offset:3072
	global_load_lds_dwordx4 v[216:217], off
	v_lshl_add_u64 v[218:219], s[70:71], 0, v[142:143]
	s_add_i32 m0, s12, 0x2000
	s_nop 0
	global_load_lds_dwordx4 v[218:219], off
	s_barrier
; #define PG8_STAGE(bufoff, gbase, voff) do { _Pragma("unroll") for (int _i = 0; _i < 2; ++_i) \
;         __builtin_amdgcn_global_load_lds((const unsigned*)((const char*)(gbase) + (voff)[_i]), (LAS unsigned*)(lds + (bufoff) + ldsw + _i * 8192), 16, 0, 0); } while (0)
; #define PG8_LDA(dst, b, h) do { _Pragma("unroll") for (int m = 0; m < 4; ++m) _Pragma("unroll") for (int k = 0; k < 2; ++k) dst[m][k] = *(const LAS bf16x8*)(lds + PG8_SA(b, h) + aoff + m * 2048 + k * 1024); } while (0)
; #define PG8_LDB(dst, b, h) do { _Pragma("unroll") for (int n = 0; n < 2; ++n) _Pragma("unroll") for (int k = 0; k < 2; ++k) dst[n][k] = *(const LAS bf16x8*)(lds + PG8_SB(b, h) + boff + n * 2048 + k * 1024); } while (0)
; #define PG8_MMA(ai, bj, At, Bt) do { __builtin_amdgcn_s_setprio(1); _Pragma("unroll") for (int m = 0; m < 4; ++m) _Pragma("unroll") for (int n = 0; n < 2; ++n) _Pragma("unroll") for (int k = 0; k < 2; ++k) \
;         acc[ai][bj][m][n] = __builtin_amdgcn_mfma_f32_16x16x32_bf16(Bt[n][k], At[m][k], acc[ai][bj][m][n], 0, 0, 0); __builtin_amdgcn_s_setprio(0); } while (0)
; #define PG8_WAIT_V(n) asm volatile("s_waitcnt vmcnt(" #n ")" ::: "memory")
; #define PG8_WAIT_L(n) asm volatile("s_waitcnt lgkmcnt(" #n ")" ::: "memory")
; #define PG8_BAR __builtin_amdgcn_s_barrier()
; #define PG8_SCHED __builtin_amdgcn_sched_barrier(0)
; template <class Epi, class Sched>
; __device__ __forceinline__ void gemm_phase(LAS unsigned char* lds, const int K, const Sched& S, const Epi& E) {
;     ...
;             PG8_BAR; PG8_WAIT_L(0); PG8_MMA(0, 1, At, B1); PG8_BAR;
;             PG8_LDA(At, 0, 1); PG8_STAGE(PG8_SA(0, 0), a2, voffA);
;             PG8_BAR; PG8_WAIT_L(0); PG8_MMA(1, 0, At, B0); PG8_BAR; PG8_SCHED;
;             PG8_STAGE(PG8_SB(0, 1), b2 + hstep, voffB);
;             PG8_WAIT_V(6); PG8_BAR; PG8_MMA(1, 1, At, B1); PG8_BAR;
;             PG8_LDB(B0, 1, 0); PG8_SCHED; PG8_LDA(At, 1, 0); PG8_STAGE(PG8_SA(0, 1), a2 + hstepA, voffA);
;             PG8_WAIT_L(8); PG8_BAR; PG8_WAIT_L(0); PG8_MMA(0, 0, At, B0); PG8_BAR; PG8_SCHED;
;             PG8_LDB(B1, 1, 1); PG8_STAGE(PG8_SB(1, 0), b3, voffB);
	s_waitcnt lgkmcnt(0)
	s_setprio 1
	s_waitcnt lgkmcnt(0)
	v_mfma_f32_16x16x32_bf16 v[60:63], v[200:203], v[166:169], v[60:63]
	v_mfma_f32_16x16x32_bf16 v[16:19], v[208:211], v[166:169], v[16:19]
	v_mfma_f32_16x16x32_bf16 v[56:59], v[200:203], v[176:179], v[56:59]
	v_mfma_f32_16x16x32_bf16 v[12:15], v[208:211], v[176:179], v[12:15]
	v_mfma_f32_16x16x32_bf16 v[52:55], v[200:203], v[184:187], v[52:55]
	v_mfma_f32_16x16x32_bf16 v[28:31], v[208:211], v[184:187], v[28:31]
	v_mfma_f32_16x16x32_bf16 v[48:51], v[200:203], v[192:195], v[48:51]
	v_mfma_f32_16x16x32_bf16 v[24:27], v[208:211], v[192:195], v[24:27]
	v_mfma_f32_16x16x32_bf16 v[60:63], v[204:207], v[172:175], v[60:63]
	v_mfma_f32_16x16x32_bf16 v[16:19], v[212:215], v[172:175], v[16:19]
	v_mfma_f32_16x16x32_bf16 v[56:59], v[204:207], v[180:183], v[56:59]
	v_mfma_f32_16x16x32_bf16 v[12:15], v[212:215], v[180:183], v[12:15]
	s_barrier
	v_mfma_f32_16x16x32_bf16 v[52:55], v[204:207], v[188:191], v[52:55]
	v_mfma_f32_16x16x32_bf16 v[28:31], v[212:215], v[188:191], v[28:31]
	v_mfma_f32_16x16x32_bf16 v[48:51], v[204:207], v[196:199], v[48:51]
	v_mfma_f32_16x16x32_bf16 v[24:27], v[212:215], v[196:199], v[24:27]
	s_setprio 0
	s_mov_b32 m0, s67
	v_lshl_add_u64 v[220:221], s[72:73], 0, v[136:137]
	ds_read_b128 v[166:169], v159 offset:16384
	ds_read_b128 v[172:175], v159 offset:17408
	ds_read_b128 v[176:179], v159 offset:18432
	ds_read_b128 v[180:183], v159 offset:19456
	ds_read_b128 v[184:187], v159 offset:20480
	ds_read_b128 v[188:191], v159 offset:21504
	ds_read_b128 v[192:195], v159 offset:22528
	ds_read_b128 v[196:199], v159 offset:23552
	global_load_lds_dwordx4 v[220:221], off
	v_lshl_add_u64 v[222:223], s[72:73], 0, v[140:141]
	s_mov_b32 m0, s80
	s_nop 0
	global_load_lds_dwordx4 v[222:223], off
	s_barrier
	s_waitcnt lgkmcnt(0)
	s_setprio 1
	s_waitcnt lgkmcnt(0)
	v_mfma_f32_16x16x32_bf16 v[112:115], v[128:131], v[166:169], v[112:115]
	v_mfma_f32_16x16x32_bf16 v[88:91], v[148:151], v[166:169], v[88:91]
	v_mfma_f32_16x16x32_bf16 v[104:107], v[128:131], v[176:179], v[104:107]
	v_mfma_f32_16x16x32_bf16 v[80:83], v[148:151], v[176:179], v[80:83]
	v_mfma_f32_16x16x32_bf16 v[100:103], v[128:131], v[184:187], v[100:103]
	v_mfma_f32_16x16x32_bf16 v[64:67], v[148:151], v[184:187], v[64:67]
	v_mfma_f32_16x16x32_bf16 v[108:111], v[128:131], v[192:195], v[108:111]
	v_mfma_f32_16x16x32_bf16 v[68:71], v[148:151], v[192:195], v[68:71]
	v_mfma_f32_16x16x32_bf16 v[112:115], v[132:135], v[172:175], v[112:115]
	v_mfma_f32_16x16x32_bf16 v[88:91], v[162:165], v[172:175], v[88:91]
	v_mfma_f32_16x16x32_bf16 v[104:107], v[132:135], v[180:183], v[104:107]
	v_mfma_f32_16x16x32_bf16 v[80:83], v[162:165], v[180:183], v[80:83]
	s_barrier
	v_mfma_f32_16x16x32_bf16 v[100:103], v[132:135], v[188:191], v[100:103]
	v_mfma_f32_16x16x32_bf16 v[64:67], v[162:165], v[188:191], v[64:67]
	v_mfma_f32_16x16x32_bf16 v[108:111], v[132:135], v[196:199], v[108:111]
	v_mfma_f32_16x16x32_bf16 v[68:71], v[162:165], v[196:199], v[68:71]
	s_setprio 0
	s_add_u32 s12, s70, 0x40000
	s_addc_u32 s13, s71, 0
	s_add_i32 s52, s89, s78
	v_lshl_add_u64 v[128:129], s[12:13], 0, v[138:139]
	s_mov_b32 m0, s52
	s_nop 0
	global_load_lds_dwordx4 v[128:129], off
	v_lshl_add_u64 v[128:129], s[12:13], 0, v[142:143]
	s_add_i32 m0, s52, 0x2000
	s_nop 0
	global_load_lds_dwordx4 v[128:129], off
	s_waitcnt vmcnt(6)
	s_barrier
	s_setprio 1
	v_mfma_f32_16x16x32_bf16 v[44:47], v[200:203], v[166:169], v[44:47]
	v_mfma_f32_16x16x32_bf16 v[20:23], v[208:211], v[166:169], v[20:23]
	v_mfma_f32_16x16x32_bf16 v[40:43], v[200:203], v[176:179], v[40:43]
	v_mfma_f32_16x16x32_bf16 v[8:11], v[208:211], v[176:179], v[8:11]
	v_mfma_f32_16x16x32_bf16 v[36:39], v[200:203], v[184:187], v[36:39]
	v_mfma_f32_16x16x32_bf16 v[0:3], v[208:211], v[184:187], v[0:3]
	v_mfma_f32_16x16x32_bf16 v[32:35], v[200:203], v[192:195], v[32:35]
	v_mfma_f32_16x16x32_bf16 v[4:7], v[208:211], v[192:195], v[4:7]
	v_mfma_f32_16x16x32_bf16 v[44:47], v[204:207], v[172:175], v[44:47]
	v_mfma_f32_16x16x32_bf16 v[20:23], v[212:215], v[172:175], v[20:23]
	v_mfma_f32_16x16x32_bf16 v[40:43], v[204:207], v[180:183], v[40:43]
	v_mfma_f32_16x16x32_bf16 v[8:11], v[212:215], v[180:183], v[8:11]
	s_barrier
	v_mfma_f32_16x16x32_bf16 v[36:39], v[204:207], v[188:191], v[36:39]
	v_mfma_f32_16x16x32_bf16 v[0:3], v[212:215], v[188:191], v[0:3]
	v_mfma_f32_16x16x32_bf16 v[32:35], v[204:207], v[196:199], v[32:35]
	v_mfma_f32_16x16x32_bf16 v[4:7], v[212:215], v[196:199], v[4:7]
	s_setprio 0
	s_add_i32 s52, 0, 0x18000
	v_add_u32_e32 v161, s52, v156
	ds_read_b128 v[128:131], v161
	ds_read_b128 v[132:135], v161 offset:1024
	ds_read_b128 v[148:151], v161 offset:2048
	ds_read_b128 v[162:165], v161 offset:3072
	s_add_u32 s12, s72, 0x20000
	s_addc_u32 s13, s73, 0
	s_mov_b32 m0, s81
	v_lshl_add_u64 v[200:201], s[12:13], 0, v[136:137]
	ds_read_b128 v[166:169], v159 offset:32768
	ds_read_b128 v[172:175], v159 offset:33792
	ds_read_b128 v[176:179], v159 offset:34816
	ds_read_b128 v[180:183], v159 offset:35840
	ds_read_b128 v[184:187], v159 offset:36864
	ds_read_b128 v[188:191], v159 offset:37888
	ds_read_b128 v[192:195], v159 offset:38912
	ds_read_b128 v[196:199], v159 offset:39936
	global_load_lds_dwordx4 v[200:201], off
	v_lshl_add_u64 v[200:201], s[12:13], 0, v[140:141]
	s_mov_b32 m0, s82
	s_nop 0
	global_load_lds_dwordx4 v[200:201], off
	s_waitcnt lgkmcnt(8)
	s_barrier
; __device__ __forceinline__ unsigned cvt_pk_bf16(float lo, float hi) { unsigned r; asm volatile("v_cvt_pk_bf16_f32 %0, %1, %2" : "=v"(r) : "v"(lo), "v"(hi)); return r; }
; #define PG8_STAGE(bufoff, gbase, voff) do { _Pragma("unroll") for (int _i = 0; _i < 2; ++_i) \
;         __builtin_amdgcn_global_load_lds((const unsigned*)((const char*)(gbase) + (voff)[_i]), (LAS unsigned*)(lds + (bufoff) + ldsw + _i * 8192), 16, 0, 0); } while (0)
; template <class Epi, class Sched>
; __device__ __forceinline__ void gemm_phase(LAS unsigned char* lds, const int K, const Sched& S, const Epi& E) {
;     ...
;             PG8_WAIT_L(8); PG8_BAR; PG8_WAIT_L(0); PG8_MMA(0, 0, At, B0); PG8_BAR; PG8_SCHED;
;             PG8_LDB(B1, 1, 1); PG8_STAGE(PG8_SB(1, 0), b3, voffB);
;             PG8_BAR; PG8_WAIT_L(0); PG8_MMA(0, 1, At, B1); PG8_BAR;
;             PG8_LDA(At, 1, 1); PG8_STAGE(PG8_SA(1, 0), a3, voffA);
;             PG8_BAR; PG8_WAIT_L(0); PG8_MMA(1, 0, At, B0); PG8_BAR; PG8_SCHED;
;             PG8_STAGE(PG8_SB(1, 1), b3 + hstep, voffB);
;             PG8_WAIT_V(6); PG8_BAR; PG8_MMA(1, 1, At, B1); PG8_BAR;
;     __device__ __forceinline__ void operator()(f32x4 (&acc)[2][2][4][2], const Unit& u, int wr, int wc, int fr, int fq) const {
;         const int J0 = u.pn * 128 + wc * 32 + fq * 8, sc = u.pm * 2 + wr;
;         const bool f0 = (fr == 0), f15 = (fr == 15);
;         if (f0 || f15) {
; #pragma unroll
;             for (int bj = 0; bj < 2; ++bj)
; #pragma unroll
;                 for (int q = 0; q < 2; ++q) { const f32x4 a0 = f0 ? acc[0][bj][q][0] : acc[1][bj][2 + q][0], a1 = f0 ? acc[0][bj][q][1] : acc[1][bj][2 + q][1];
;                     u32x4 w; w.x = cvt_pk_bf16(a0[0], a0[1]); w.y = cvt_pk_bf16(a0[2], a0[3]); w.z = cvt_pk_bf16(a1[0], a1[1]); w.w = cvt_pk_bf16(a1[2], a1[3]);
;                     *(u32x4*)(side + (size_t)(sc * 4 + (f0 ? q : 2 + q)) * (2 * DFF) + bj * DFF + J0) = w; }
;         }
; #pragma unroll
;         for (int bj = 0; bj < 2; ++bj)
; #pragma unroll
;             for (int n = 0; n < 2; ++n) {
;                 const int col = bj * DFF + J0 + n * 4;
;                 const float csc = bj ? 0.6931471805599453f : 1.4426950408889634f;
;                 const f32x4 k0 = *(const f32x4*)(cw + col) * csc, k1 = *(const f32x4*)(cw + 2 * DFF + col) * csc, k2 = *(const f32x4*)(cw + 4 * DFF + col) * csc, kb = *(const f32x4*)(cb + col) * csc;
	s_waitcnt lgkmcnt(0)
	s_setprio 1
	s_waitcnt lgkmcnt(0)
	v_mfma_f32_16x16x32_bf16 v[84:87], v[128:131], v[166:169], v[84:87]
	v_mfma_f32_16x16x32_bf16 v[76:79], v[148:151], v[166:169], v[76:79]
	v_mfma_f32_16x16x32_bf16 v[124:127], v[128:131], v[176:179], v[124:127]
	v_mfma_f32_16x16x32_bf16 v[72:75], v[148:151], v[176:179], v[72:75]
	v_mfma_f32_16x16x32_bf16 v[120:123], v[128:131], v[184:187], v[120:123]
	v_mfma_f32_16x16x32_bf16 v[96:99], v[148:151], v[184:187], v[96:99]
	v_mfma_f32_16x16x32_bf16 v[116:119], v[128:131], v[192:195], v[116:119]
	v_mfma_f32_16x16x32_bf16 v[92:95], v[148:151], v[192:195], v[92:95]
	v_mfma_f32_16x16x32_bf16 v[84:87], v[132:135], v[172:175], v[84:87]
	v_mfma_f32_16x16x32_bf16 v[76:79], v[162:165], v[172:175], v[76:79]
	v_mfma_f32_16x16x32_bf16 v[124:127], v[132:135], v[180:183], v[124:127]
	v_mfma_f32_16x16x32_bf16 v[72:75], v[162:165], v[180:183], v[72:75]
	s_barrier
	v_mfma_f32_16x16x32_bf16 v[120:123], v[132:135], v[188:191], v[120:123]
	v_mfma_f32_16x16x32_bf16 v[96:99], v[162:165], v[188:191], v[96:99]
	v_mfma_f32_16x16x32_bf16 v[116:119], v[132:135], v[196:199], v[116:119]
	v_mfma_f32_16x16x32_bf16 v[92:95], v[162:165], v[196:199], v[92:95]
	s_setprio 0
	s_add_i32 s53, 0, 0x1c000
	s_add_i32 s12, s52, s78
	v_add_u32_e32 v161, s53, v156
	v_lshl_add_u64 v[216:217], v[216:217], 0, s[38:39]
	s_mov_b32 m0, s12
	ds_read_b128 v[200:203], v161
	ds_read_b128 v[204:207], v161 offset:1024
	ds_read_b128 v[208:211], v161 offset:2048
	ds_read_b128 v[212:215], v161 offset:3072
	global_load_lds_dwordx4 v[216:217], off
	v_lshl_add_u64 v[216:217], v[218:219], 0, s[38:39]
	s_add_i32 m0, s12, 0x2000
	s_nop 0
	global_load_lds_dwordx4 v[216:217], off
	s_barrier
	s_waitcnt lgkmcnt(0)
	s_setprio 1
	s_waitcnt lgkmcnt(0)
	v_mfma_f32_16x16x32_bf16 v[60:63], v[200:203], v[166:169], v[60:63]
	v_mfma_f32_16x16x32_bf16 v[16:19], v[208:211], v[166:169], v[16:19]
	v_mfma_f32_16x16x32_bf16 v[56:59], v[200:203], v[176:179], v[56:59]
	v_mfma_f32_16x16x32_bf16 v[12:15], v[208:211], v[176:179], v[12:15]
	v_mfma_f32_16x16x32_bf16 v[52:55], v[200:203], v[184:187], v[52:55]
	v_mfma_f32_16x16x32_bf16 v[28:31], v[208:211], v[184:187], v[28:31]
	v_mfma_f32_16x16x32_bf16 v[48:51], v[200:203], v[192:195], v[48:51]
	v_mfma_f32_16x16x32_bf16 v[24:27], v[208:211], v[192:195], v[24:27]
	v_mfma_f32_16x16x32_bf16 v[60:63], v[204:207], v[172:175], v[60:63]
	v_mfma_f32_16x16x32_bf16 v[16:19], v[212:215], v[172:175], v[16:19]
	v_mfma_f32_16x16x32_bf16 v[56:59], v[204:207], v[180:183], v[56:59]
	v_mfma_f32_16x16x32_bf16 v[12:15], v[212:215], v[180:183], v[12:15]
	s_barrier
	v_mfma_f32_16x16x32_bf16 v[52:55], v[204:207], v[188:191], v[52:55]
	v_mfma_f32_16x16x32_bf16 v[28:31], v[212:215], v[188:191], v[28:31]
	v_mfma_f32_16x16x32_bf16 v[48:51], v[204:207], v[196:199], v[48:51]
	v_mfma_f32_16x16x32_bf16 v[24:27], v[212:215], v[196:199], v[24:27]
	s_setprio 0
	s_mov_b32 m0, s84
	v_lshl_add_u64 v[216:217], v[220:221], 0, s[38:39]
	ds_read_b128 v[166:169], v159 offset:49152
	ds_read_b128 v[172:175], v159 offset:50176
	ds_read_b128 v[176:179], v159 offset:51200
	ds_read_b128 v[180:183], v159 offset:52224
	ds_read_b128 v[184:187], v159 offset:53248
	ds_read_b128 v[188:191], v159 offset:54272
	ds_read_b128 v[192:195], v159 offset:55296
	ds_read_b128 v[196:199], v159 offset:56320
	global_load_lds_dwordx4 v[216:217], off
	v_lshl_add_u64 v[216:217], v[222:223], 0, s[38:39]
	s_mov_b32 m0, s85
	s_nop 0
	global_load_lds_dwordx4 v[216:217], off
	s_barrier
	s_waitcnt lgkmcnt(0)
	s_setprio 1
	s_waitcnt lgkmcnt(0)
	v_mfma_f32_16x16x32_bf16 v[112:115], v[128:131], v[166:169], v[112:115]
	v_mfma_f32_16x16x32_bf16 v[88:91], v[148:151], v[166:169], v[88:91]
	v_mfma_f32_16x16x32_bf16 v[104:107], v[128:131], v[176:179], v[104:107]
	v_mfma_f32_16x16x32_bf16 v[80:83], v[148:151], v[176:179], v[80:83]
	v_mfma_f32_16x16x32_bf16 v[100:103], v[128:131], v[184:187], v[100:103]
	v_mfma_f32_16x16x32_bf16 v[64:67], v[148:151], v[184:187], v[64:67]
	v_mfma_f32_16x16x32_bf16 v[108:111], v[128:131], v[192:195], v[108:111]
	v_mfma_f32_16x16x32_bf16 v[68:71], v[148:151], v[192:195], v[68:71]
	v_mfma_f32_16x16x32_bf16 v[112:115], v[132:135], v[172:175], v[112:115]
	v_mfma_f32_16x16x32_bf16 v[88:91], v[162:165], v[172:175], v[88:91]
	v_mfma_f32_16x16x32_bf16 v[104:107], v[132:135], v[180:183], v[104:107]
	v_mfma_f32_16x16x32_bf16 v[80:83], v[162:165], v[180:183], v[80:83]
	s_barrier
	v_mfma_f32_16x16x32_bf16 v[100:103], v[132:135], v[188:191], v[100:103]
	v_mfma_f32_16x16x32_bf16 v[64:67], v[162:165], v[188:191], v[64:67]
	v_mfma_f32_16x16x32_bf16 v[108:111], v[132:135], v[196:199], v[108:111]
	v_mfma_f32_16x16x32_bf16 v[68:71], v[162:165], v[196:199], v[68:71]
	s_setprio 0
	s_add_u32 s12, s70, 0x40080
	s_addc_u32 s13, s71, 0
	s_add_i32 s52, s53, s78
	v_lshl_add_u64 v[128:129], s[12:13], 0, v[138:139]
	s_mov_b32 m0, s52
	s_nop 0
	global_load_lds_dwordx4 v[128:129], off
	v_lshl_add_u64 v[128:129], s[12:13], 0, v[142:143]
	s_add_i32 m0, s52, 0x2000
	s_nop 0
	global_load_lds_dwordx4 v[128:129], off
	s_waitcnt vmcnt(6)
	s_barrier
	s_setprio 1
	v_mfma_f32_16x16x32_bf16 v[44:47], v[200:203], v[166:169], v[44:47]
	v_mfma_f32_16x16x32_bf16 v[20:23], v[208:211], v[166:169], v[20:23]
	v_mfma_f32_16x16x32_bf16 v[40:43], v[200:203], v[176:179], v[40:43]
	v_mfma_f32_16x16x32_bf16 v[8:11], v[208:211], v[176:179], v[8:11]
	v_mfma_f32_16x16x32_bf16 v[36:39], v[200:203], v[184:187], v[36:39]
	v_mfma_f32_16x16x32_bf16 v[0:3], v[208:211], v[184:187], v[0:3]
	v_mfma_f32_16x16x32_bf16 v[32:35], v[200:203], v[192:195], v[32:35]
	v_mfma_f32_16x16x32_bf16 v[4:7], v[208:211], v[192:195], v[4:7]
	v_mfma_f32_16x16x32_bf16 v[44:47], v[204:207], v[172:175], v[44:47]
	v_mfma_f32_16x16x32_bf16 v[20:23], v[212:215], v[172:175], v[20:23]
	v_mfma_f32_16x16x32_bf16 v[40:43], v[204:207], v[180:183], v[40:43]
	v_mfma_f32_16x16x32_bf16 v[8:11], v[212:215], v[180:183], v[8:11]
	s_barrier
	v_mfma_f32_16x16x32_bf16 v[36:39], v[204:207], v[188:191], v[36:39]
	v_mfma_f32_16x16x32_bf16 v[0:3], v[212:215], v[188:191], v[0:3]
	v_mfma_f32_16x16x32_bf16 v[32:35], v[204:207], v[196:199], v[32:35]
	v_mfma_f32_16x16x32_bf16 v[4:7], v[212:215], v[196:199], v[4:7]
	s_setprio 0
	s_add_i32 s49, s49, 2
	s_add_u32 s11, s11, 0x100
	s_addc_u32 s33, s33, 0
	s_cmp_gt_u32 s49, 13
	s_mov_b64 s[12:13], s[68:69]
	s_cbranch_scc0 .LBB0_800
	v_lshl_or_b32 v150, s10, 7, v157
	v_add_u32_e32 v254, 0x2c00, v253
	global_load_dwordx4 v[208:211], v253, s[22:23] offset:16
	global_load_dwordx4 v[212:215], v253, s[24:25] offset:16
	global_load_dwordx4 v[216:219], v253, s[26:27] offset:16
	global_load_dwordx4 v[220:223], v253, s[36:37] offset:16
	v_cmp_gt_i32_e32 vcc, 15, v152
	s_mov_b64 s[70:71], -1
	s_and_saveexec_b64 s[68:69], vcc
	s_cbranch_execz .LBB0_805
	v_cmp_eq_u32_e32 vcc, 0, v152
	v_cmp_ne_u32_e64 s[12:13], 0, v152
	s_and_saveexec_b64 s[70:71], s[12:13]
	v_ashrrev_i32_e32 v151, 31, v150
	v_mov_b64_e32 v[148:149], v[150:151]
	s_or_b64 exec, exec, s[70:71]
	s_orn2_b64 s[70:71], vcc, exec
